# S8 plus L2 prefetch of the unit's gate rows (one dummy dword load per lane) at masked-loop entry
# baseline (speedup 1.0000x reference)
; #define ATT_TOP(t) do { if ((t) + 2 < NT) ATT_LOADK((t) + 2); if ((t) + 1 < NT) ATT_LOADV((t) + 1); } while (0)
; #define ATT_BOT(t) do { if ((t) + 2 < NT) ATT_STOREK(k2); if ((t) + 1 < NT) ATT_STOREV(v1); __syncthreads(); \
;         { const int kk = k0; k0 = k1; k1 = k2; k2 = kk; const int vv = v0; v0 = v1; v1 = vv; } } while (0)
; #define ATT_RESC() do { if (__any(alpha_n < 1.f)) { _Pragma("unroll") for (int i = 0; i < 4; ++i) _Pragma("unroll") for (int r = 0; r < 16; ++r) o[i][r] *= alpha_n; } } while (0)
; __device__ __forceinline__ void unit(LAS unsigned char* lds, int b, int h, int qb, const bf16_t* Q, const bf16_t* Kn, const bf16_t* Kr, const bf16_t* VT, const bf16_t* proj, bf16_t* ymix, int wv) {
;     ...
;     for (; t + 1 < NT; ++t) { ATT_TOP(t); ATT_QKN(k1); __builtin_amdgcn_sched_barrier(0); ATT_FUSED(t + 1, true); ATT_RESC(); ATT_BOT(t); }
;     ...
;         for (int g = 0; g < 4; ++g) gts[blk][g] = *(const u32x2*)(proj + tok * NIN + PJ_BG + h * 128 + 32 * blk + 8 * g + 4 * hi);
.LBB0_620:
	s_lshl_b32 s73, s62, 2
	s_add_i32 s73, s73, 4
	s_add_i32 s8, s63, 1
	s_mov_b32 s55, s13
	s_cmp_ge_u32 s8, s73
	s_cbranch_scc1 .LBB0_604
	v_add_u32_e32 v252, s54, v216
	v_mov_b32_e32 v250, s22
	v_mov_b32_e32 v251, s23
	v_mad_u64_u32 v[250:251], vcc, v252, s66, v[250:251]
	v_lshlrev_b32_e32 v252, 5, v225
	v_lshl_add_u32 v252, s69, 1, v252
	v_add_u32_e32 v252, 0x1000, v252
	v_mov_b32_e32 v253, 0
	v_lshl_add_u64 v[250:251], v[250:251], 0, v[252:253]
	global_load_dword v253, v[250:251], off
	s_lshl_b32 s8, s63, 6
	s_add_i32 s58, s8, 0xa0
	s_add_i32 s74, s63, 2

; #define ATT_TOP(t) do { if ((t) + 2 < NT) ATT_LOADK((t) + 2); if ((t) + 1 < NT) ATT_LOADV((t) + 1); } while (0)
; #define ATT_BOT(t) do { if ((t) + 2 < NT) ATT_STOREK(k2); if ((t) + 1 < NT) ATT_STOREV(v1); __syncthreads(); \
;         { const int kk = k0; k0 = k1; k1 = k2; k2 = kk; const int vv = v0; v0 = v1; v1 = vv; } } while (0)
; #define ATT_RESC() do { if (__any(alpha_n < 1.f)) { _Pragma("unroll") for (int i = 0; i < 4; ++i) _Pragma("unroll") for (int r = 0; r < 16; ++r) o[i][r] *= alpha_n; } } while (0)
; __device__ __forceinline__ void unit(LAS unsigned char* lds, int b, int h, int qb, const bf16_t* Q, const bf16_t* Kn, const bf16_t* Kr, const bf16_t* VT, const bf16_t* proj, bf16_t* ymix, int wv) {
;     ...
;     for (; t + 1 < NT; ++t) { ATT_TOP(t); ATT_QKN(k1); __builtin_amdgcn_sched_barrier(0); ATT_FUSED(t + 1, true); ATT_RESC(); ATT_BOT(t); }
;     ...
;         for (int g = 0; g < 4; ++g) gts[blk][g] = *(const u32x2*)(proj + tok * NIN + PJ_BG + h * 128 + 32 * blk + 8 * g + 4 * hi);
.LBB0_1185:
	s_lshl_b32 s60, s40, 2
	s_add_i32 s60, s60, 4
	s_add_i32 s6, s41, 1
	s_mov_b32 s17, s7
	s_cmp_ge_u32 s6, s60
	s_cbranch_scc1 .LBB0_1169
	v_add_u32_e32 v252, s16, v216
	v_mov_b32_e32 v250, s46
	v_mov_b32_e32 v251, s47
	v_mad_u64_u32 v[250:251], vcc, v252, s54, v[250:251]
	v_lshlrev_b32_e32 v252, 5, v225
	v_lshl_add_u32 v252, s56, 1, v252
	v_add_u32_e32 v252, 0x1000, v252
	v_mov_b32_e32 v253, 0
	v_lshl_add_u64 v[250:251], v[250:251], 0, v[252:253]
	global_load_dword v253, v[250:251], off
	s_lshl_b32 s6, s41, 6
	s_add_i32 s36, s6, 0xa0
	s_add_i32 s61, s41, 2
